# mlstm scan alpha: eight serially waited exec-masked decay-weight blocks replaced by one batched computation (b128 read, cndmask causal mask)
# speedup vs baseline: 1.0446x; 1.0080x over previous
.LBB0_436:
	s_waitcnt lgkmcnt(0)
	ds_read_b128 v[194:197], v142
	ds_read_b32 v198, v166
	ds_read_b32 v199, v167
	v_mov_b32_e32 v80, 0
	v_mov_b32_e32 v81, 0
	v_mov_b32_e32 v82, 0
	v_mov_b32_e32 v83, 0
	s_and_saveexec_b64 s[92:93], s[12:13]
	s_cbranch_execz .LBB0_438
	ds_read_b128 v[80:83], v100 offset:17408
	ds_read_b128 v[116:119], v100 offset:17472
	ds_read_b128 v[178:181], v169
	ds_read_b128 v[182:185], v169 offset:64
	s_waitcnt lgkmcnt(1)
	v_mfma_f32_16x16x32_bf16 v[80:83], v[80:83], v[178:181], 0
	ds_read_b128 v[178:181], v100 offset:17536
	ds_read_b128 v[186:189], v100 offset:17600
	s_waitcnt lgkmcnt(2)
	v_mfma_f32_16x16x32_bf16 v[80:83], v[116:119], v[182:185], v[80:83]
	ds_read_b128 v[116:119], v169 offset:128
	ds_read_b128 v[182:185], v169 offset:192
	s_waitcnt lgkmcnt(1)
	v_mfma_f32_16x16x32_bf16 v[80:83], v[178:181], v[116:119], v[80:83]
	s_waitcnt lgkmcnt(0)
	v_mfma_f32_16x16x32_bf16 v[80:83], v[186:189], v[182:185], v[80:83]
.LBB0_438:
	s_or_b64 exec, exec, s[92:93]
	global_load_dwordx4 v[64:67], v[0:1], off
	v_add_co_u32_e32 v0, vcc, 0x400, v0
	s_nop 1
	v_addc_co_u32_e32 v1, vcc, 0, v1, vcc
	s_waitcnt lgkmcnt(0)
	v_sub_f32_e32 v200, v194, v198
	v_sub_f32_e32 v201, v195, v198
	v_sub_f32_e32 v202, v196, v198
	v_sub_f32_e32 v203, v197, v198
	v_min_f32_e32 v200, 0, v200
	v_min_f32_e32 v201, 0, v201
	v_min_f32_e32 v202, 0, v202
	v_min_f32_e32 v203, 0, v203
	v_mul_f32_e32 v200, 0x3fb8aa3b, v200
	v_mul_f32_e32 v201, 0x3fb8aa3b, v201
	v_mul_f32_e32 v202, 0x3fb8aa3b, v202
	v_mul_f32_e32 v203, 0x3fb8aa3b, v203
	v_exp_f32_e32 v200, v200
	v_exp_f32_e32 v201, v201
	v_exp_f32_e32 v202, v202
	v_exp_f32_e32 v203, v203
	v_mul_f32_e32 v200, v80, v200
	v_mul_f32_e32 v201, v81, v201
	v_mul_f32_e32 v202, v82, v202
	v_mul_f32_e32 v203, v83, v203
	v_cndmask_b32_e64 v200, 0, v200, s[40:41]
	v_cndmask_b32_e64 v201, 0, v201, s[42:43]
	v_cndmask_b32_e64 v202, 0, v202, s[44:45]
	v_cndmask_b32_e64 v203, 0, v203, s[46:47]
	v_cvt_pk_bf16_f32 v82, v200, v201
	v_cvt_pk_bf16_f32 v83, v202, v203
	ds_write_b64 v170, v[82:83]
	global_load_dwordx4 v[32:35], v[240:241], off
	global_load_dwordx4 v[36:39], v[240:241], off offset:2048
	v_lshl_add_u64 v[240:241], v[240:241], 0, s[98:99]
	v_mov_b32_e32 v80, 0
	v_mov_b32_e32 v81, 0
	v_mov_b32_e32 v82, 0
	v_mov_b32_e32 v83, 0
	s_and_saveexec_b64 s[92:93], s[14:15]
	s_cbranch_execz .LBB0_448
	ds_read_b128 v[80:83], v100 offset:17408
	ds_read_b128 v[116:119], v100 offset:17472
	ds_read_b128 v[178:181], v171
	ds_read_b128 v[182:185], v171 offset:64
	s_waitcnt lgkmcnt(1)
	v_mfma_f32_16x16x32_bf16 v[80:83], v[80:83], v[178:181], 0
	ds_read_b128 v[178:181], v100 offset:17536
	ds_read_b128 v[186:189], v100 offset:17600
	s_waitcnt lgkmcnt(2)
	v_mfma_f32_16x16x32_bf16 v[80:83], v[116:119], v[182:185], v[80:83]
	ds_read_b128 v[116:119], v171 offset:128
	ds_read_b128 v[182:185], v171 offset:192
	s_waitcnt lgkmcnt(1)
	v_mfma_f32_16x16x32_bf16 v[80:83], v[178:181], v[116:119], v[80:83]
	s_waitcnt lgkmcnt(0)
	v_mfma_f32_16x16x32_bf16 v[80:83], v[186:189], v[182:185], v[80:83]
.LBB0_448:
	s_or_b64 exec, exec, s[92:93]
	global_load_dwordx4 v[44:47], v[244:245], off
	global_load_dwordx4 v[48:51], v[244:245], off offset:2048
	v_lshl_add_u64 v[244:245], v[244:245], 0, s[98:99]
	v_sub_f32_e32 v200, v194, v199
	v_sub_f32_e32 v201, v195, v199
	v_sub_f32_e32 v202, v196, v199
	v_sub_f32_e32 v203, v197, v199
	v_min_f32_e32 v200, 0, v200
	v_min_f32_e32 v201, 0, v201
	v_min_f32_e32 v202, 0, v202
	v_min_f32_e32 v203, 0, v203
	v_mul_f32_e32 v200, 0x3fb8aa3b, v200
	v_mul_f32_e32 v201, 0x3fb8aa3b, v201
	v_mul_f32_e32 v202, 0x3fb8aa3b, v202
	v_mul_f32_e32 v203, 0x3fb8aa3b, v203
	v_exp_f32_e32 v200, v200
	v_exp_f32_e32 v201, v201
	v_exp_f32_e32 v202, v202
	v_exp_f32_e32 v203, v203
	v_mul_f32_e32 v200, v80, v200
	v_mul_f32_e32 v201, v81, v201
	v_mul_f32_e32 v202, v82, v202
	v_mul_f32_e32 v203, v83, v203
	v_cndmask_b32_e64 v200, 0, v200, s[48:49]
	v_cndmask_b32_e64 v201, 0, v201, s[50:51]
	v_cndmask_b32_e64 v202, 0, v202, s[52:53]
	v_cndmask_b32_e64 v203, 0, v203, s[54:55]
	v_cvt_pk_bf16_f32 v82, v200, v201
	v_cvt_pk_bf16_f32 v83, v202, v203
	ds_write_b64 v172, v[82:83]
	ds_read_b128 v[80:83], v100
	ds_read_b128 v[116:119], v101 offset:34816
	ds_read_b128 v[178:181], v100 offset:64
	ds_read_b128 v[182:185], v101 offset:34880
	ds_read_b128 v[186:189], v253 offset:43520
	ds_read_b128 v[190:193], v253 offset:43584
	s_waitcnt lgkmcnt(4)
	v_mfma_f32_16x16x32_bf16 v[116:119], v[80:83], v[116:119], 0
	v_mul_f32_e64 v70, v70, v114
	v_mul_f32_e64 v71, v71, v114
	v_pk_mul_f32 v[68:69], v[68:69], v[114:115] op_sel_hi:[1,0]
	v_pk_mul_f32 v[78:79], v[78:79], v[114:115] op_sel_hi:[1,0]
	s_waitcnt lgkmcnt(2)
	v_mfma_f32_16x16x32_bf16 v[116:119], v[178:181], v[182:185], v[116:119]
	ds_read_b128 v[182:185], v100 offset:128
	v_pk_mul_f32 v[76:77], v[76:77], v[114:115] op_sel_hi:[1,0]
	v_pk_mul_f32 v[74:75], v[74:75], v[114:115] op_sel_hi:[1,0]
	s_waitcnt lgkmcnt(2)
	v_mfma_f32_16x16x32_bf16 v[80:83], v[80:83], v[186:189], 0
	v_mul_f32_e64 v72, v72, v114
	v_mul_f32_e64 v73, v73, v114
	s_waitcnt lgkmcnt(1)
	v_mfma_f32_16x16x32_bf16 v[80:83], v[178:181], v[190:193], v[80:83]
	ds_read_b128 v[178:181], v101 offset:34944
	ds_read_b128 v[186:189], v100 offset:192
	ds_read_b128 v[190:193], v101 offset:35008
	s_waitcnt lgkmcnt(2)
	v_mfma_f32_16x16x32_bf16 v[116:119], v[182:185], v[178:181], v[116:119]
	ds_read_b128 v[178:181], v253 offset:43648
	ds_read_b128 v[194:197], v253 offset:43712
	s_waitcnt lgkmcnt(0)
	s_barrier
	v_mfma_f32_16x16x32_bf16 v[80:83], v[182:185], v[178:181], v[80:83]
	ds_read_b128 v[178:181], v146
	ds_read_b128 v[182:185], v147
	v_mfma_f32_16x16x32_bf16 v[80:83], v[186:189], v[194:197], v[80:83]
	s_waitcnt lgkmcnt(0)
	v_max_f32_e32 v252, v182, v182
	v_mfma_f32_16x16x32_bf16 v[116:119], v[186:189], v[190:193], v[116:119]
	ds_read_b128 v[186:189], v127
	ds_read_b128 v[190:193], v127 offset:64
	ds_read_b128 v[194:197], v128
	ds_read_b128 v[198:201], v128 offset:64
	ds_read_b128 v[202:205], v254 offset:4608
	ds_read_b128 v[206:209], v254 offset:4672
	v_pk_mul_f32 v[82:83], v[82:83], v[180:181]
	v_pk_mul_f32 v[80:81], v[80:81], v[178:179]
	v_pk_mul_f32 v[118:119], v[118:119], v[180:181]
	v_pk_mul_f32 v[116:117], v[116:117], v[178:179]
	s_waitcnt lgkmcnt(1)
	v_mfma_f32_16x16x32_bf16 v[80:83], v[186:189], v[202:205], v[80:83]
	v_add_u32_e32 v180, v103, v129
	ds_read_b128 v[202:205], v102 offset:47872
	ds_read_b128 v[210:213], v102 offset:47936
	ds_read_b128 v[214:217], v180
	ds_read_b128 v[218:221], v180 offset:64
	s_waitcnt vmcnt(7)
	ds_bpermute_b32 v182, v124, v56
	s_waitcnt lgkmcnt(5)
	v_mfma_f32_16x16x32_bf16 v[80:83], v[190:193], v[206:209], v[80:83]
	global_load_dwordx4 v[40:43], v[242:243], off
	v_lshl_add_u64 v[242:243], v[242:243], 0, s[100:101]
	ds_read_b128 v[206:209], v173
	ds_read_b128 v[222:225], v173 offset:64
	ds_read_b128 v[226:229], v173 offset:2304
	ds_read_b128 v[230:233], v173 offset:2368
	v_mfma_f32_16x16x32_bf16 v[116:119], v[186:189], v[194:197], v[116:119]
	s_nop 2
	v_max_f32_e64 v251, |v80|, |v80|
	v_max_f32_e32 v80, v183, v183
	s_waitcnt lgkmcnt(0)
	v_max_f32_e64 v251, |v251|, |v251|
	v_max_f32_e32 v251, v251, v252
	v_max_f32_e64 v252, |v81|, |v81|
	v_rcp_f32_e32 v251, v251
	v_mfma_f32_16x16x32_bf16 v[116:119], v[190:193], v[198:201], v[116:119]
	global_load_dwordx4 v[52:55], v[246:247], off
	v_lshl_add_u64 v[246:247], v[246:247], 0, s[100:101]
	s_waitcnt lgkmcnt(0)
	v_max_f32_e64 v252, |v252|, |v252|
	v_max_f32_e32 v252, v252, v80
	v_rcp_f32_e32 v252, v252
	v_max_f32_e64 v80, |v82|, |v82|
	s_nop 2
	v_mul_f32_e32 v251, v116, v251
	v_cvt_pk_bf16_f32 v251, v251, s0
	ds_write_b16 v174, v251
	v_mul_f32_e32 v251, v117, v252
	v_cvt_pk_bf16_f32 v251, v251, s0
	ds_write_b16 v174, v251 offset:80
	s_waitcnt lgkmcnt(2)
	v_max_f32_e64 v251, |v80|, |v80|
	v_max_f32_e32 v252, v184, v184
	v_max_f32_e32 v251, v251, v252
	v_max_f32_e64 v252, |v83|, |v83|
	v_rcp_f32_e32 v251, v251
	v_mfma_f32_16x16x32_bf16 v[80:83], v[202:205], v[226:229], v[68:71]
	s_waitcnt lgkmcnt(0)
	v_max_f32_e64 v252, |v252|, |v252|
	s_nop 0
	v_max_f32_e32 v68, v185, v185
	v_max_f32_e32 v252, v252, v68
	v_rcp_f32_e32 v252, v252
	v_mfma_f32_16x16x32_bf16 v[76:79], v[202:205], v[214:217], v[76:79]
	s_mov_b64 s[94:95], exec
	s_mov_b64 exec, s[4:5]
	global_load_dwordx4 v[60:63], v[248:249], off
	s_mov_b64 exec, s[94:95]
	v_lshl_add_u64 v[248:249], v[248:249], 0, s[98:99]
	v_mul_f32_e32 v251, v118, v251
	v_cvt_pk_bf16_f32 v251, v251, s0
	ds_write_b16 v174, v251 offset:160
	v_mfma_f32_16x16x32_bf16 v[72:75], v[202:205], v[206:209], v[72:75]
	v_mul_f32_e32 v251, v119, v252
	v_cvt_pk_bf16_f32 v251, v251, s0
	ds_write_b16 v174, v251 offset:240
	v_mfma_f32_16x16x32_bf16 v[76:79], v[210:213], v[218:221], v[76:79]
	v_max_f32_e32 v251, v177, v177
	v_max_f32_e32 v252, v58, v58
	v_max_f32_e32 v251, v251, v252
	v_mfma_f32_16x16x32_bf16 v[68:71], v[210:213], v[222:225], v[72:75]
	ds_bpermute_b32 v181, v124, v251
	v_mfma_f32_16x16x32_bf16 v[72:75], v[210:213], v[230:233], v[80:83]
	s_nop 2
	v_cvt_pk_bf16_f32 v80, v76, v77
	v_cvt_pk_bf16_f32 v81, v78, v79
	ds_write_b64 v175, v[80:81] offset:34816
	v_cvt_pk_bf16_f32 v80, v68, v69
	v_cvt_pk_bf16_f32 v81, v70, v71
	ds_write_b64 v176, v[80:81] offset:34816
	v_cvt_pk_bf16_f32 v80, v72, v73
	v_cvt_pk_bf16_f32 v81, v74, v75
	ds_write_b64 v176, v[80:81] offset:39168
	s_and_saveexec_b64 s[92:93], s[6:7]
	s_cbranch_execz .LBB0_456
	ds_write_b32 v133, v57
	ds_write_b32 v132, v251

.LBB0_469:
	v_sub_f32_e32 v251, v177, v181
	v_mul_f32_e32 v251, 0x3fb8aa3b, v251
	v_exp_f32_e32 v114, v251
	s_waitcnt lgkmcnt(2)
	ds_read_b128 v[204:207], v142
	ds_read_b32 v208, v166
	ds_read_b32 v209, v167
	v_mov_b32_e32 v80, 0
	v_mov_b32_e32 v81, 0
	v_mov_b32_e32 v82, 0
	v_mov_b32_e32 v83, 0
	s_and_saveexec_b64 s[92:93], s[12:13]
	s_cbranch_execz .LBB0_471
	ds_read_b128 v[80:83], v100 offset:17408
	ds_read_b128 v[184:187], v100 offset:17472
	ds_read_b128 v[188:191], v169
	ds_read_b128 v[192:195], v169 offset:64
	s_waitcnt lgkmcnt(1)
	v_mfma_f32_16x16x32_bf16 v[80:83], v[80:83], v[188:191], 0
	ds_read_b128 v[188:191], v100 offset:17536
	ds_read_b128 v[196:199], v100 offset:17600
	s_waitcnt lgkmcnt(2)
	v_mfma_f32_16x16x32_bf16 v[80:83], v[184:187], v[192:195], v[80:83]
	ds_read_b128 v[184:187], v169 offset:128
	ds_read_b128 v[192:195], v169 offset:192
	s_waitcnt lgkmcnt(1)
	v_mfma_f32_16x16x32_bf16 v[80:83], v[188:191], v[184:187], v[80:83]
	s_waitcnt lgkmcnt(0)
	v_mfma_f32_16x16x32_bf16 v[80:83], v[196:199], v[192:195], v[80:83]
.LBB0_471:
	s_or_b64 exec, exec, s[92:93]
	global_load_dwordx4 v[56:59], v[0:1], off
	v_add_co_u32_e32 v0, vcc, 0x400, v0
	s_nop 1
	v_addc_co_u32_e32 v1, vcc, 0, v1, vcc
	s_waitcnt lgkmcnt(0)
	v_sub_f32_e32 v210, v204, v208
	v_sub_f32_e32 v211, v205, v208
	v_sub_f32_e32 v212, v206, v208
	v_sub_f32_e32 v213, v207, v208
	v_min_f32_e32 v210, 0, v210
	v_min_f32_e32 v211, 0, v211
	v_min_f32_e32 v212, 0, v212
	v_min_f32_e32 v213, 0, v213
	v_mul_f32_e32 v210, 0x3fb8aa3b, v210
	v_mul_f32_e32 v211, 0x3fb8aa3b, v211
	v_mul_f32_e32 v212, 0x3fb8aa3b, v212
	v_mul_f32_e32 v213, 0x3fb8aa3b, v213
	v_exp_f32_e32 v210, v210
	v_exp_f32_e32 v211, v211
	v_exp_f32_e32 v212, v212
	v_exp_f32_e32 v213, v213
	v_mul_f32_e32 v210, v80, v210
	v_mul_f32_e32 v211, v81, v211
	v_mul_f32_e32 v212, v82, v212
	v_mul_f32_e32 v213, v83, v213
	v_cndmask_b32_e64 v210, 0, v210, s[40:41]
	v_cndmask_b32_e64 v211, 0, v211, s[42:43]
	v_cndmask_b32_e64 v212, 0, v212, s[44:45]
	v_cndmask_b32_e64 v213, 0, v213, s[46:47]
	v_cvt_pk_bf16_f32 v82, v210, v211
	v_cvt_pk_bf16_f32 v83, v212, v213
	ds_write_b64 v170, v[82:83]
	global_load_dwordx4 v[8:11], v[240:241], off
	global_load_dwordx4 v[12:15], v[240:241], off offset:2048
	v_lshl_add_u64 v[240:241], v[240:241], 0, s[98:99]
	v_mov_b32_e32 v80, 0
	v_mov_b32_e32 v81, 0
	v_mov_b32_e32 v82, 0
	v_mov_b32_e32 v83, 0
	s_and_saveexec_b64 s[92:93], s[14:15]
	s_cbranch_execz .LBB0_481
	ds_read_b128 v[80:83], v100 offset:17408
	ds_read_b128 v[184:187], v100 offset:17472
	ds_read_b128 v[188:191], v171
	ds_read_b128 v[192:195], v171 offset:64
	s_waitcnt lgkmcnt(1)
	v_mfma_f32_16x16x32_bf16 v[80:83], v[80:83], v[188:191], 0
	ds_read_b128 v[188:191], v100 offset:17536
	ds_read_b128 v[196:199], v100 offset:17600
	s_waitcnt lgkmcnt(2)
	v_mfma_f32_16x16x32_bf16 v[80:83], v[184:187], v[192:195], v[80:83]
	ds_read_b128 v[184:187], v171 offset:128
	ds_read_b128 v[192:195], v171 offset:192
	s_waitcnt lgkmcnt(1)
	v_mfma_f32_16x16x32_bf16 v[80:83], v[188:191], v[184:187], v[80:83]
	s_waitcnt lgkmcnt(0)
	v_mfma_f32_16x16x32_bf16 v[80:83], v[196:199], v[192:195], v[80:83]
.LBB0_481:
	s_or_b64 exec, exec, s[92:93]
	global_load_dwordx4 v[20:23], v[244:245], off
	global_load_dwordx4 v[24:27], v[244:245], off offset:2048
	v_lshl_add_u64 v[244:245], v[244:245], 0, s[98:99]
	v_sub_f32_e32 v210, v204, v209
	v_sub_f32_e32 v211, v205, v209
	v_sub_f32_e32 v212, v206, v209
	v_sub_f32_e32 v213, v207, v209
	v_min_f32_e32 v210, 0, v210
	v_min_f32_e32 v211, 0, v211
	v_min_f32_e32 v212, 0, v212
	v_min_f32_e32 v213, 0, v213
	v_mul_f32_e32 v210, 0x3fb8aa3b, v210
	v_mul_f32_e32 v211, 0x3fb8aa3b, v211
	v_mul_f32_e32 v212, 0x3fb8aa3b, v212
	v_mul_f32_e32 v213, 0x3fb8aa3b, v213
	v_exp_f32_e32 v210, v210
	v_exp_f32_e32 v211, v211
	v_exp_f32_e32 v212, v212
	v_exp_f32_e32 v213, v213
	v_mul_f32_e32 v210, v80, v210
	v_mul_f32_e32 v211, v81, v211
	v_mul_f32_e32 v212, v82, v212
	v_mul_f32_e32 v213, v83, v213
	v_cndmask_b32_e64 v210, 0, v210, s[48:49]
	v_cndmask_b32_e64 v211, 0, v211, s[50:51]
	v_cndmask_b32_e64 v212, 0, v212, s[52:53]
	v_cndmask_b32_e64 v213, 0, v213, s[54:55]
	v_cvt_pk_bf16_f32 v82, v210, v211
	v_cvt_pk_bf16_f32 v83, v212, v213
	ds_write_b64 v172, v[82:83]
	ds_read_b128 v[80:83], v100
	ds_read_b128 v[184:187], v101 offset:34816
	ds_read_b128 v[188:191], v100 offset:64
	ds_read_b128 v[192:195], v101 offset:34880
	ds_read_b128 v[196:199], v253 offset:43520
	ds_read_b128 v[200:203], v253 offset:43584
	s_waitcnt lgkmcnt(4)
	v_mfma_f32_16x16x32_bf16 v[184:187], v[80:83], v[184:187], 0
	v_add_f32_e32 v177, v181, v182
	v_pk_mul_f32 v[78:79], v[78:79], v[114:115] op_sel_hi:[1,0]
	v_pk_mul_f32 v[76:77], v[76:77], v[114:115] op_sel_hi:[1,0]
	s_waitcnt lgkmcnt(1)
	v_mfma_f32_16x16x32_bf16 v[80:83], v[80:83], v[196:199], 0
	v_mul_f32_e64 v70, v70, v114
	v_mul_f32_e64 v71, v71, v114
	v_pk_mul_f32 v[68:69], v[68:69], v[114:115] op_sel_hi:[1,0]
	v_pk_mul_f32 v[74:75], v[74:75], v[114:115] op_sel_hi:[1,0]
	v_mfma_f32_16x16x32_bf16 v[184:187], v[188:191], v[192:195], v[184:187]
	ds_read_b128 v[192:195], v100 offset:128
	ds_read_b128 v[196:199], v101 offset:34944
	v_pk_mul_f32 v[72:73], v[72:73], v[114:115] op_sel_hi:[1,0]
	s_add_i32 s72, s1, 1
	s_waitcnt lgkmcnt(2)
	v_mfma_f32_16x16x32_bf16 v[80:83], v[188:191], v[200:203], v[80:83]
	ds_read_b128 v[188:191], v253 offset:43648
	ds_read_b128 v[200:203], v100 offset:192
	ds_read_b128 v[204:207], v101 offset:35008
	s_cmpk_lt_u32 s72, 0x7f
	s_cselect_b64 s[92:93], -1, 0
	s_waitcnt lgkmcnt(3)
	v_mfma_f32_16x16x32_bf16 v[184:187], v[192:195], v[196:199], v[184:187]
	ds_read_b128 v[196:199], v253 offset:43712
	s_waitcnt lgkmcnt(0)
	s_barrier
	v_mfma_f32_16x16x32_bf16 v[80:83], v[192:195], v[188:191], v[80:83]
	ds_read_b128 v[188:191], v147
	ds_read_b128 v[192:195], v146
	s_cmpk_gt_u32 s72, 0x7e
	v_mfma_f32_16x16x32_bf16 v[80:83], v[200:203], v[196:199], v[80:83]
	ds_read_b128 v[196:199], v127
	v_mfma_f32_16x16x32_bf16 v[182:185], v[200:203], v[204:207], v[184:187]
	ds_read_b128 v[200:203], v254 offset:4608
	ds_read_b128 v[204:207], v127 offset:64
	ds_read_b128 v[208:211], v128
	ds_read_b128 v[212:215], v128 offset:64
	ds_read_b128 v[216:219], v254 offset:4672
	s_waitcnt lgkmcnt(6)
	v_pk_mul_f32 v[82:83], v[82:83], v[194:195]
	v_pk_mul_f32 v[80:81], v[80:81], v[192:193]
	v_pk_mul_f32 v[184:185], v[184:185], v[194:195]
	v_pk_mul_f32 v[182:183], v[182:183], v[192:193]
	s_waitcnt lgkmcnt(4)
	v_mfma_f32_16x16x32_bf16 v[80:83], v[196:199], v[200:203], v[80:83]
	ds_read_b128 v[192:195], v102 offset:47872
	ds_read_b128 v[200:203], v102 offset:47936
	ds_read_b128 v[220:223], v180
	ds_read_b128 v[224:227], v180 offset:64
	s_waitcnt lgkmcnt(4)
	v_mfma_f32_16x16x32_bf16 v[80:83], v[204:207], v[216:219], v[80:83]
	global_load_dwordx4 v[16:19], v[242:243], off
	v_lshl_add_u64 v[242:243], v[242:243], 0, s[100:101]
	ds_read_b128 v[216:219], v173
	ds_read_b128 v[228:231], v173 offset:64
	ds_read_b128 v[232:235], v173 offset:2304
	ds_read_b128 v[236:239], v173 offset:2368
	v_mfma_f32_16x16x32_bf16 v[180:183], v[196:199], v[208:211], v[182:185]
	s_nop 2
	v_max_f32_e64 v251, |v80|, |v80|
	v_max_f32_e32 v80, v188, v188
	v_max_f32_e64 v111, |v83|, |v83|
	v_mfma_f32_16x16x32_bf16 v[180:183], v[204:207], v[212:215], v[180:183]
	global_load_dwordx4 v[28:31], v[246:247], off
	v_lshl_add_u64 v[246:247], v[246:247], 0, s[100:101]
	s_waitcnt lgkmcnt(0)
	v_max_f32_e64 v251, |v251|, |v251|
	v_max_f32_e32 v251, v251, v80
	v_max_f32_e64 v80, |v81|, |v81|
	v_rcp_f32_e32 v251, v251
	v_max_f32_e32 v81, v189, v189
	v_mfma_f32_16x16x32_bf16 v[76:79], v[192:195], v[220:223], v[76:79]
	s_waitcnt lgkmcnt(0)
	v_max_f32_e64 v80, |v80|, |v80|
	v_max_f32_e32 v80, v80, v81
	v_rcp_f32_e32 v80, v80
	v_max_f32_e64 v81, |v82|, |v82|
	v_mul_f32_e32 v251, v180, v251
	v_cvt_pk_bf16_f32 v251, v251, s0
	ds_write_b16 v174, v251
	v_mul_f32_e32 v251, v181, v80
	v_cvt_pk_bf16_f32 v251, v251, s0
	ds_write_b16 v174, v251 offset:80
	s_waitcnt lgkmcnt(2)
	v_max_f32_e64 v251, |v81|, |v81|
	v_max_f32_e32 v80, v190, v190
	v_max_f32_e32 v251, v251, v80
	v_rcp_f32_e32 v251, v251
	v_mfma_f32_16x16x32_bf16 v[68:71], v[192:195], v[216:219], v[68:71]
	s_mov_b64 s[94:95], exec
	s_mov_b64 exec, s[4:5]
	global_load_dwordx4 v[4:7], v[248:249], off
	s_mov_b64 exec, s[94:95]
	v_lshl_add_u64 v[248:249], v[248:249], 0, s[98:99]
	v_mul_f32_e32 v251, v182, v251
	v_mfma_f32_16x16x32_bf16 v[80:83], v[192:195], v[232:235], v[72:75]
	v_cvt_pk_bf16_f32 v251, v251, s0
	ds_write_b16 v174, v251 offset:160
	s_nop 0
	v_max_f32_e64 v72, |v111|, |v111|
	v_max_f32_e32 v73, v191, v191
	v_max_f32_e32 v72, v72, v73
	v_rcp_f32_e32 v111, v72
	v_mfma_f32_16x16x32_bf16 v[76:79], v[200:203], v[224:227], v[76:79]
	v_mul_f32_e32 v251, v183, v111
	v_mfma_f32_16x16x32_bf16 v[72:75], v[200:203], v[228:231], v[68:71]
	v_cvt_pk_bf16_f32 v251, v251, s0
	ds_write_b16 v174, v251 offset:240
	v_mfma_f32_16x16x32_bf16 v[68:71], v[200:203], v[236:239], v[80:83]
	s_nop 2
	v_cvt_pk_bf16_f32 v80, v76, v77
	v_cvt_pk_bf16_f32 v81, v78, v79
	ds_write_b64 v175, v[80:81] offset:34816
	v_cvt_pk_bf16_f32 v80, v72, v73
	v_cvt_pk_bf16_f32 v81, v74, v75
	ds_write_b64 v176, v[80:81] offset:34816
	v_cvt_pk_bf16_f32 v80, v68, v69
	v_cvt_pk_bf16_f32 v81, v70, v71
	ds_write_b64 v176, v[80:81] offset:39168
	s_cbranch_scc1 .LBB0_493
	s_waitcnt vmcnt(9)
	v_max_f32_e32 v251, v177, v177
	v_max_f32_e32 v252, v66, v66
	v_max_f32_e32 v81, v251, v252
	ds_bpermute_b32 v251, v124, v81
	ds_bpermute_b32 v80, v124, v64
	s_and_saveexec_b64 s[94:95], s[6:7]
	s_cbranch_execz .LBB0_492
	ds_write_b32 v133, v65
	ds_write_b32 v132, v81

.LBB0_504:
	s_branch .LBB0_435
.LBB0_509:
	s_waitcnt vmcnt(0)
	v_mov_b32_e32 v0, v85
	v_mov_b32_e32 v1, v85
	v_mov_b32_e32 v2, v85
	v_mov_b32_e32 v3, v85
	s_mov_b64 s[0:1], 0
	s_movk_i32 s25, 0x110
